# speedup vs baseline: 1.0071x; 1.0018x over previous
; #define MFMA_FENCE() do { __builtin_amdgcn_sched_barrier(0); asm volatile("s_nop 15\n\ts_nop 15" ::: "memory"); __builtin_amdgcn_sched_barrier(0); } while (0)
; DEVI f32x16 mfma32(bf16x8 a, bf16x8 b, f32x16 c) { return __builtin_amdgcn_mfma_f32_32x32x16_bf16(a, b, c, 0, 0, 0); }
; template <bool SBK>
; __device__ __forceinline__ void attn_item(KP p, int layer, int b, int hh, int qt, char* smem, int tix) {
;     ...
;     if (kt * 64 <= qmax_w && !sb_done) {
;       f32x16 s[2];
;       __builtin_amdgcn_s_setprio(1);
; #pragma unroll
;       for (int kb2 = 0; kb2 < 2; ++kb2) {
; #pragma unroll
;         for (int r = 0; r < 16; ++r) s[kb2][r] = 0.f;
; #pragma unroll
;         for (int ks = 0; ks < 4; ++ks) {
;           bf16x8 a = *(const bf16x8*)(kb + (kb2 * 32 + l32) * KST + c * 64 + ks * 16 + hf * 8);
;           s[kb2] = mfma32(a, qf[ks], s[kb2]);
;         }
;       }
;       __builtin_amdgcn_s_setprio(0);
;       bf16x8 pf[2][2];
;       MFMA_FENCE();
;       if (!SBK) {
;         const bool need_mask = (kt * 64 + 63 > qmin_w) || (kt == 1);
;         float mx = -1e30f;
; #pragma unroll
;         for (int kb2 = 0; kb2 < 2; ++kb2)
; #pragma unroll
;           for (int r = 0; r < 16; ++r) {
;             float t = s[kb2][r] * sc2;
;             if (need_mask) {
;               int kp = kt * 64 + kb2 * 32 + 8 * (r >> 2) + 4 * hf + (r & 3);
;               if (kp < PADF || kp > qpos) t = -1e30f;
;             }
;             s[kb2][r] = t;
;             mx = fmaxf(mx, t);
;           }
.LBB0_389:
	s_or_b64 exec, exec, s[6:7]
	s_sub_i32 s6, s14, 64
	v_cmp_le_i32_e32 vcc, s6, v141
	s_and_saveexec_b64 s[18:19], vcc
	s_cbranch_execz .LBB0_393
	s_bitcmp1_b32 s8, 0
	s_cselect_b32 s7, 0x2200, 0
	s_lshl_b32 s15, s7, 1
	v_add3_u32 v161, v151, s15, v157
	ds_read_b128 v[194:197], v161
	ds_read_b128 v[198:201], v161 offset:32
	ds_read_b128 v[202:205], v161 offset:64
	ds_read_b128 v[206:209], v161 offset:96
	ds_read_b128 v[210:213], v161 offset:8704
	ds_read_b128 v[214:217], v161 offset:8736
	ds_read_b128 v[218:221], v161 offset:8768
	ds_read_b128 v[222:225], v161 offset:8800
	s_waitcnt lgkmcnt(7)
	v_mfma_f32_32x32x16_bf16 v[82:97], v[194:197], v[98:101], 0
	s_waitcnt lgkmcnt(6)
	v_mfma_f32_32x32x16_bf16 v[82:97], v[198:201], v[102:105], v[82:97]
	s_waitcnt lgkmcnt(5)
	v_mfma_f32_32x32x16_bf16 v[82:97], v[202:205], v[106:109], v[82:97]
	s_waitcnt lgkmcnt(4)
	v_mfma_f32_32x32x16_bf16 v[82:97], v[206:209], v[110:113], v[82:97]
	s_waitcnt lgkmcnt(3)
	v_mfma_f32_32x32x16_bf16 v[66:81], v[210:213], v[98:101], 0
	s_waitcnt lgkmcnt(2)
	v_mfma_f32_32x32x16_bf16 v[66:81], v[214:217], v[102:105], v[66:81]
	s_waitcnt lgkmcnt(1)
	v_mfma_f32_32x32x16_bf16 v[66:81], v[218:221], v[106:109], v[66:81]
	s_waitcnt lgkmcnt(0)
	v_mfma_f32_32x32x16_bf16 v[66:81], v[222:225], v[110:113], v[66:81]
	v_add3_u32 v242, v152, s15, v159
	v_add_u32_e32 v243, 0x8800, v242
	ds_read2_b64 v[194:197], v243 offset1:2
	ds_read2_b64 v[198:201], v243 offset0:4 offset1:6
	ds_read2_b64 v[202:205], v243 offset0:8 offset1:10
	ds_read2_b64 v[206:209], v243 offset0:12 offset1:14
	v_add_u32_e32 v243, 0x9800, v242
	ds_read2_b64 v[210:213], v243 offset0:32 offset1:34
	ds_read2_b64 v[214:217], v243 offset0:36 offset1:38
	ds_read2_b64 v[218:221], v243 offset0:40 offset1:42
	ds_read2_b64 v[222:225], v243 offset0:44 offset1:46
	v_add_u32_e32 v243, 0xa800, v242
	ds_read2_b64 v[226:229], v243 offset0:64 offset1:66
	ds_read2_b64 v[230:233], v243 offset0:68 offset1:70
	ds_read2_b64 v[234:237], v243 offset0:72 offset1:74
	ds_read2_b64 v[238:241], v243 offset0:76 offset1:78
	s_nop 3
	s_add_i32 s7, s14, -1
	v_add_u32_e32 v161, s14, v134
	v_subrev_u32_e32 v162, 64, v161
	s_cmpk_lt_u32 s6, 0x70
	v_cmp_gt_i32_e32 vcc, s7, v148
	s_cbranch_vccz .Ldiff_fast
	s_cselect_b64 s[8:9], -1, 0
	v_cmp_gt_i32_e64 s[6:7], v162, v133
	s_or_b64 s[6:7], s[8:9], s[6:7]
	v_mul_f32_e32 v82, 0x3e38aa3b, v82
	s_and_b64 s[6:7], vcc, s[6:7]
	v_cndmask_b32_e64 v82, v82, v182, s[6:7]
	v_cmp_ge_i32_e64 s[6:7], v162, v133
	s_or_b64 s[6:7], s[8:9], s[6:7]
	v_mul_f32_e32 v83, 0x3e38aa3b, v83
	s_and_b64 s[6:7], vcc, s[6:7]
	v_subrev_u32_e32 v163, 62, v161
	v_cndmask_b32_e64 v83, v83, v182, s[6:7]
	v_cmp_gt_i32_e64 s[6:7], v163, v133
	s_or_b64 s[6:7], s[8:9], s[6:7]
	v_mul_f32_e32 v84, 0x3e38aa3b, v84
	s_and_b64 s[6:7], vcc, s[6:7]
	v_subrev_u32_e32 v163, 61, v161
	v_cndmask_b32_e64 v84, v84, v182, s[6:7]
	v_cmp_gt_i32_e64 s[6:7], v163, v133
	s_or_b64 s[6:7], s[8:9], s[6:7]
	v_mul_f32_e32 v85, 0x3e38aa3b, v85
	s_and_b64 s[6:7], vcc, s[6:7]
	v_subrev_u32_e32 v163, 56, v161
	v_cndmask_b32_e64 v85, v85, v182, s[6:7]
	v_cmp_gt_i32_e64 s[6:7], v163, v133
	s_or_b64 s[6:7], s[8:9], s[6:7]
	v_mul_f32_e32 v86, 0x3e38aa3b, v86
	s_and_b64 s[6:7], vcc, s[6:7]
	v_subrev_u32_e32 v163, 55, v161
	v_cndmask_b32_e64 v86, v86, v182, s[6:7]
	v_cmp_gt_i32_e64 s[6:7], v163, v133
	s_or_b64 s[6:7], s[8:9], s[6:7]
	v_mul_f32_e32 v87, 0x3e38aa3b, v87
	s_and_b64 s[6:7], vcc, s[6:7]
	v_subrev_u32_e32 v163, 54, v161
	v_cndmask_b32_e64 v87, v87, v182, s[6:7]
	v_cmp_gt_i32_e64 s[6:7], v163, v133
	s_or_b64 s[6:7], s[8:9], s[6:7]
	v_mul_f32_e32 v88, 0x3e38aa3b, v88
	s_and_b64 s[6:7], vcc, s[6:7]
	v_subrev_u32_e32 v163, 53, v161
	v_cndmask_b32_e64 v88, v88, v182, s[6:7]
	v_cmp_gt_i32_e64 s[6:7], v163, v133
	s_or_b64 s[6:7], s[8:9], s[6:7]
	v_mul_f32_e32 v89, 0x3e38aa3b, v89
	s_and_b64 s[6:7], vcc, s[6:7]
	v_subrev_u32_e32 v163, 48, v161
	v_cndmask_b32_e64 v89, v89, v182, s[6:7]
	v_cmp_gt_u32_e64 s[6:7], s53, v163
	v_cmp_gt_i32_e64 s[8:9], v163, v133
	s_or_b64 s[6:7], s[6:7], s[8:9]
	v_mul_f32_e32 v90, 0x3e38aa3b, v90
	s_and_b64 s[6:7], vcc, s[6:7]
	v_subrev_u32_e32 v163, 47, v161
	v_cndmask_b32_e64 v90, v90, v182, s[6:7]
	v_cmp_gt_u32_e64 s[6:7], s53, v163
	v_cmp_gt_i32_e64 s[8:9], v163, v133
	s_or_b64 s[6:7], s[6:7], s[8:9]
	v_mul_f32_e32 v91, 0x3e38aa3b, v91
	s_and_b64 s[6:7], vcc, s[6:7]
	v_subrev_u32_e32 v163, 46, v161
	v_cndmask_b32_e64 v91, v91, v182, s[6:7]
	v_cmp_gt_u32_e64 s[6:7], s53, v163
	v_cmp_gt_i32_e64 s[8:9], v163, v133
	s_or_b64 s[6:7], s[6:7], s[8:9]
	v_mul_f32_e32 v92, 0x3e38aa3b, v92
	s_and_b64 s[6:7], vcc, s[6:7]
	v_subrev_u32_e32 v163, 45, v161
	v_cndmask_b32_e64 v92, v92, v182, s[6:7]
	v_cmp_gt_u32_e64 s[6:7], s53, v163
	v_cmp_gt_i32_e64 s[8:9], v163, v133
	s_or_b64 s[6:7], s[6:7], s[8:9]
	v_mul_f32_e32 v93, 0x3e38aa3b, v93
	s_and_b64 s[6:7], vcc, s[6:7]
	v_subrev_u32_e32 v163, 40, v161
	v_cndmask_b32_e64 v93, v93, v182, s[6:7]
	v_cmp_gt_u32_e64 s[6:7], s53, v163
	v_cmp_gt_i32_e64 s[8:9], v163, v133
	s_or_b64 s[6:7], s[6:7], s[8:9]
	v_mul_f32_e32 v94, 0x3e38aa3b, v94
	s_and_b64 s[6:7], vcc, s[6:7]
	v_subrev_u32_e32 v163, 39, v161
	v_cndmask_b32_e64 v94, v94, v182, s[6:7]
; DEVI float max32x(float v) { float a, b; swap32(v, a, b); return fmaxf(a, b); }
; template <bool SBK>
; __device__ __forceinline__ void attn_item(KP p, int layer, int b, int hh, int qt, char* smem, int tix) {
;     ...
;       if (!SBK) {
;         const bool need_mask = (kt * 64 + 63 > qmin_w) || (kt == 1);
;         float mx = -1e30f;
; #pragma unroll
;         for (int kb2 = 0; kb2 < 2; ++kb2)
; #pragma unroll
;           for (int r = 0; r < 16; ++r) {
;             float t = s[kb2][r] * sc2;
;             if (need_mask) {
;               int kp = kt * 64 + kb2 * 32 + 8 * (r >> 2) + 4 * hf + (r & 3);
;               if (kp < PADF || kp > qpos) t = -1e30f;
;             }
;             s[kb2][r] = t;
;             mx = fmaxf(mx, t);
;           }
;         mx = max32x(mx);
	v_cmp_gt_u32_e64 s[6:7], s53, v163
	v_cmp_gt_i32_e64 s[8:9], v163, v133
	s_or_b64 s[6:7], s[6:7], s[8:9]
	v_mul_f32_e32 v95, 0x3e38aa3b, v95
	s_and_b64 s[6:7], vcc, s[6:7]
	v_subrev_u32_e32 v163, 38, v161
	v_cndmask_b32_e64 v95, v95, v182, s[6:7]
	v_cmp_gt_u32_e64 s[6:7], s53, v163
	v_cmp_gt_i32_e64 s[8:9], v163, v133
	s_or_b64 s[6:7], s[6:7], s[8:9]
	v_mul_f32_e32 v96, 0x3e38aa3b, v96
	s_and_b64 s[6:7], vcc, s[6:7]
	v_subrev_u32_e32 v163, 37, v161
	v_cndmask_b32_e64 v96, v96, v182, s[6:7]
	v_cmp_gt_u32_e64 s[6:7], s53, v163
	v_cmp_gt_i32_e64 s[8:9], v163, v133
	s_or_b64 s[6:7], s[6:7], s[8:9]
	v_mul_f32_e32 v97, 0x3e38aa3b, v97
	s_and_b64 s[6:7], vcc, s[6:7]
	v_subrev_u32_e32 v163, 32, v161
	v_cndmask_b32_e64 v97, v97, v182, s[6:7]
	v_cmp_gt_u32_e64 s[6:7], s53, v163
	v_cmp_gt_i32_e64 s[8:9], v163, v133
	s_or_b64 s[6:7], s[6:7], s[8:9]
	v_mul_f32_e32 v66, 0x3e38aa3b, v66
	s_and_b64 s[6:7], vcc, s[6:7]
	v_subrev_u32_e32 v163, 31, v161
	v_cndmask_b32_e64 v66, v66, v182, s[6:7]
	v_cmp_gt_u32_e64 s[6:7], s53, v163
	v_cmp_gt_i32_e64 s[8:9], v163, v133
	s_or_b64 s[6:7], s[6:7], s[8:9]
	v_mul_f32_e32 v67, 0x3e38aa3b, v67
	s_and_b64 s[6:7], vcc, s[6:7]
	v_subrev_u32_e32 v163, 30, v161
	v_cndmask_b32_e64 v67, v67, v182, s[6:7]
	v_cmp_gt_u32_e64 s[6:7], s53, v163
	v_cmp_gt_i32_e64 s[8:9], v163, v133
	s_or_b64 s[6:7], s[6:7], s[8:9]
	v_mul_f32_e32 v68, 0x3e38aa3b, v68
	s_and_b64 s[6:7], vcc, s[6:7]
	v_subrev_u32_e32 v163, 29, v161
	v_cndmask_b32_e64 v68, v68, v182, s[6:7]
	v_cmp_gt_u32_e64 s[6:7], s53, v163
	v_cmp_gt_i32_e64 s[8:9], v163, v133
	s_or_b64 s[6:7], s[6:7], s[8:9]
	v_mul_f32_e32 v69, 0x3e38aa3b, v69
	s_and_b64 s[6:7], vcc, s[6:7]
	v_subrev_u32_e32 v163, 24, v161
	v_cndmask_b32_e64 v69, v69, v182, s[6:7]
	v_cmp_gt_u32_e64 s[6:7], s53, v163
	v_cmp_gt_i32_e64 s[8:9], v163, v133
	s_or_b64 s[6:7], s[6:7], s[8:9]
	v_mul_f32_e32 v70, 0x3e38aa3b, v70
	s_and_b64 s[6:7], vcc, s[6:7]
	v_subrev_u32_e32 v163, 23, v161
	v_cndmask_b32_e64 v70, v70, v182, s[6:7]
	v_cmp_gt_u32_e64 s[6:7], s53, v163
	v_cmp_gt_i32_e64 s[8:9], v163, v133
	s_or_b64 s[6:7], s[6:7], s[8:9]
	v_mul_f32_e32 v71, 0x3e38aa3b, v71
	s_and_b64 s[6:7], vcc, s[6:7]
	v_subrev_u32_e32 v163, 22, v161
	v_cndmask_b32_e64 v71, v71, v182, s[6:7]
	v_cmp_gt_u32_e64 s[6:7], s53, v163
	v_cmp_gt_i32_e64 s[8:9], v163, v133
	s_or_b64 s[6:7], s[6:7], s[8:9]
	v_mul_f32_e32 v72, 0x3e38aa3b, v72
	s_and_b64 s[6:7], vcc, s[6:7]
	v_subrev_u32_e32 v163, 21, v161
	v_cndmask_b32_e64 v72, v72, v182, s[6:7]
	v_cmp_gt_u32_e64 s[6:7], s53, v163
	v_cmp_gt_i32_e64 s[8:9], v163, v133
	s_or_b64 s[6:7], s[6:7], s[8:9]
	v_mul_f32_e32 v73, 0x3e38aa3b, v73
	s_and_b64 s[6:7], vcc, s[6:7]
	v_add_u32_e32 v163, -16, v161
	v_cndmask_b32_e64 v73, v73, v182, s[6:7]
	v_cmp_gt_u32_e64 s[6:7], s53, v163
	v_cmp_gt_i32_e64 s[8:9], v163, v133
	s_or_b64 s[6:7], s[6:7], s[8:9]
	v_mul_f32_e32 v74, 0x3e38aa3b, v74
	s_and_b64 s[6:7], vcc, s[6:7]
	v_add_u32_e32 v163, -15, v161
	v_cndmask_b32_e64 v74, v74, v182, s[6:7]
	v_cmp_gt_u32_e64 s[6:7], s53, v163
	v_cmp_gt_i32_e64 s[8:9], v163, v133
	s_or_b64 s[6:7], s[6:7], s[8:9]
	v_mul_f32_e32 v75, 0x3e38aa3b, v75
	s_and_b64 s[6:7], vcc, s[6:7]
	v_add_u32_e32 v163, -14, v161
	v_cndmask_b32_e64 v75, v75, v182, s[6:7]
	v_cmp_gt_u32_e64 s[6:7], s53, v163
	v_cmp_gt_i32_e64 s[8:9], v163, v133
	s_or_b64 s[6:7], s[6:7], s[8:9]
	v_mul_f32_e32 v76, 0x3e38aa3b, v76
	s_and_b64 s[6:7], vcc, s[6:7]
	v_add_u32_e32 v163, -13, v161
	v_cndmask_b32_e64 v76, v76, v182, s[6:7]
	v_cmp_gt_u32_e64 s[6:7], s53, v163
	v_cmp_gt_i32_e64 s[8:9], v163, v133
	v_max3_f32 v162, v82, s23, v83
	s_or_b64 s[6:7], s[6:7], s[8:9]
	v_max3_f32 v162, v162, v84, v85
	v_mul_f32_e32 v77, 0x3e38aa3b, v77
	s_and_b64 s[6:7], vcc, s[6:7]
	v_add_u32_e32 v163, -8, v161
	v_max3_f32 v162, v162, v86, v87
	v_cndmask_b32_e64 v77, v77, v182, s[6:7]
	v_cmp_gt_u32_e64 s[6:7], s53, v163
	v_cmp_gt_i32_e64 s[8:9], v163, v133
	v_max3_f32 v162, v162, v88, v89
	s_or_b64 s[6:7], s[6:7], s[8:9]
	v_max3_f32 v162, v162, v90, v91
	v_mul_f32_e32 v78, 0x3e38aa3b, v78
	s_and_b64 s[6:7], vcc, s[6:7]
	v_add_u32_e32 v163, -7, v161
	v_max3_f32 v162, v162, v92, v93
	v_cndmask_b32_e64 v78, v78, v182, s[6:7]
	v_cmp_gt_u32_e64 s[6:7], s53, v163
	v_cmp_gt_i32_e64 s[8:9], v163, v133
	v_max3_f32 v162, v162, v94, v95
	s_or_b64 s[6:7], s[6:7], s[8:9]
	v_max3_f32 v162, v162, v96, v97
	v_mul_f32_e32 v79, 0x3e38aa3b, v79
	s_and_b64 s[6:7], vcc, s[6:7]
	v_add_u32_e32 v163, -6, v161
	v_max3_f32 v162, v162, v66, v67
	v_cndmask_b32_e64 v79, v79, v182, s[6:7]
	v_cmp_gt_u32_e64 s[6:7], s53, v163
	v_cmp_gt_i32_e64 s[8:9], v163, v133
	v_max3_f32 v162, v162, v68, v69
	s_or_b64 s[6:7], s[6:7], s[8:9]
	v_max3_f32 v162, v162, v70, v71
	v_mul_f32_e32 v80, 0x3e38aa3b, v80
	s_and_b64 s[6:7], vcc, s[6:7]
	v_add_u32_e32 v161, -5, v161
	v_max3_f32 v162, v162, v72, v73
	v_cndmask_b32_e64 v80, v80, v182, s[6:7]
	v_cmp_gt_u32_e64 s[6:7], s53, v161
	v_cmp_gt_i32_e64 s[8:9], v161, v133
	v_max3_f32 v162, v162, v74, v75
	s_or_b64 s[6:7], s[6:7], s[8:9]
	v_max3_f32 v162, v162, v76, v77
	v_mul_f32_e32 v81, 0x3e38aa3b, v81
	s_and_b64 vcc, vcc, s[6:7]
	v_max3_f32 v162, v162, v78, v79
	v_cndmask_b32_e32 v81, v81, v182, vcc
	v_max3_f32 v161, v162, v80, v81
